# L1-only invalidate also at the FFN2-down->next-layer seam and the GLU->gate/up seam
# speedup vs baseline: 1.0067x; 1.0028x over previous
.LBB0_558:
	s_or_b64 exec, exec, s[14:15]
	s_waitcnt lgkmcnt(0)
	v_readlane_b32 s2, v255, 40
	s_nop 0
	s_cmp_lg_u32 s2, 0
	s_cbranch_scc0 .Linvf_glun
	buffer_inv sc0
	s_branch .Linvd_glun
.Linvf_glun:
	buffer_inv sc1
.Linvd_glun:
	s_waitcnt vmcnt(0)

.LBB0_589:
	s_or_b64 exec, exec, s[10:11]
	s_mov_b64 s[6:7], exec
	v_mbcnt_lo_u32_b32 v0, s6, 0
	v_mbcnt_hi_u32_b32 v0, s7, v0
	v_cmp_eq_u32_e32 vcc, 0, v0
	s_waitcnt vmcnt(0)
	v_readlane_b32 s2, v255, 40
	s_nop 0
	s_cmp_lg_u32 s2, 0
	s_cbranch_scc0 .Linvf_gluj
	buffer_inv sc0
	s_branch .Linvd_gluj
.Linvf_gluj:
	buffer_inv sc1
.Linvd_gluj:
	s_and_saveexec_b64 s[10:11], vcc
	s_cbranch_execz .LBB0_591
	s_bcnt1_i32_b64 s2, s[6:7]
	v_mov_b32_e32 v0, s2
	global_atomic_add v231, v0, s[8:9] offset:1024

.LBB0_1342:
	s_or_b64 exec, exec, s[16:17]
	s_waitcnt lgkmcnt(0)
	v_readlane_b32 s2, v255, 40
	s_nop 0
	s_cmp_lg_u32 s2, 0
	s_cbranch_scc0 .Linvf_b2n
	s_cmp_lg_u64 s[10:11], 0
	s_cbranch_scc0 .Linvf_b2n
	buffer_inv sc0
	s_branch .Linvd_b2n
.Linvf_b2n:
	buffer_inv sc1
.Linvd_b2n:
	s_waitcnt vmcnt(0)
.LBB0_1343:
	s_andn2_saveexec_b64 s[2:3], s[12:13]
	s_cbranch_execnz .LBB0_1344
	s_getpc_b64 s[98:99]

.LBB0_1373:
	s_or_b64 exec, exec, s[12:13]
	s_mov_b64 s[6:7], exec
	v_mbcnt_lo_u32_b32 v0, s6, 0
	v_mbcnt_hi_u32_b32 v0, s7, v0
	v_cmp_eq_u32_e32 vcc, 0, v0
	s_waitcnt vmcnt(0)
	v_readlane_b32 s2, v255, 40
	s_nop 0
	s_cmp_lg_u32 s2, 0
	s_cbranch_scc0 .Linvf_b2j
	s_cmp_lg_u64 s[10:11], 0
	s_cbranch_scc0 .Linvf_b2j
	buffer_inv sc0
	s_branch .Linvd_b2j

.Linvd_b2j:
	s_and_saveexec_b64 s[12:13], vcc
	s_cbranch_execnz .LBB0_1374
	s_getpc_b64 s[98:99]
